# stick-breaking attention: removed never-taken denormal/inf guards around v_log (argument is in [1,2]); bit-identical results, ~7 VALU fewer per score
# speedup vs baseline: 1.0168x; 1.0168x over previous
; #define MFMA(a, b, c) __builtin_amdgcn_mfma_f32_32x32x16_bf16((a), (b), (c), 0, 0, 0)
; DI int crow(int i, int h) { return (i & 3) + 8 * (i >> 2) + 4 * h; }
; DI void qk_tile(const bf16_t* sK, const bf16x8 (&qf)[4], f32x16 (&Sx)[2], int r, int h) {
; #pragma unroll
;   for (int mt = 0; mt < 2; ++mt) {
;     f32x16 a;
; #pragma unroll
;     for (int i = 0; i < 16; ++i) a[i] = 0.f;
; #pragma unroll
;     for (int s = 0; s < 4; ++s) {
;       const bf16x8 k = *(const bf16x8*)(sK + (mt * 32 + r) * 72 + s * 16 + h * 8);
;       a = MFMA(k, qf[s], a);
;     }
;     Sx[mt] = a;
;   }
; }
; template <bool MASKED>
; DI void sb_weights(f32x16 (&Sx)[2], float& carry, int kt, int t, int h) {
; #pragma unroll
;     ...
;         float L[16];
; #pragma unroll
;         for (int i = 0; i < 16; ++i) {
;           const float z = Sx[mt][i];
;           const bool ok = !MASKED || (kt * 64 + mt * 32 + crow(i, h) < t);
;           const float sp = fmaxf(z, 0.f) + __logf(1.f + __expf(-fabsf(z)));
;           L[i] = ok ? -sp : 0.f;
;           Sx[mt][i] = ok ? (z - sp) : NEG;
;         }
.LBB0_277:
	s_add_i32 s44, s80, 1
	v_cmp_le_i32_e64 s[0:1], s44, v177
	s_and_saveexec_b64 s[36:37], s[0:1]
	s_cbranch_execz .LBB0_283
	ds_read_b128 v[0:3], v32
	ds_read_b128 v[4:7], v32 offset:32
	v_cmp_ge_i32_e64 s[0:1], s42, v175
	v_add_f32_e32 v188, 0, v144
	s_waitcnt lgkmcnt(1)
	v_mfma_f32_32x32x16_bf16 v[66:81], v[0:3], v[106:109], 0
	ds_read_b128 v[0:3], v32 offset:4608
	ds_read_b128 v[8:11], v32 offset:4640
	s_waitcnt lgkmcnt(1)
	v_mfma_f32_32x32x16_bf16 v[82:97], v[0:3], v[106:109], 0
	s_waitcnt lgkmcnt(0)
	v_mfma_f32_32x32x16_bf16 v[82:97], v[8:11], v[98:101], v[82:97]
	ds_read_b128 v[0:3], v32 offset:4672
	ds_read_b128 v[8:11], v32 offset:64
	ds_read_b128 v[12:15], v32 offset:96
	ds_read_b128 v[16:19], v32 offset:4704
	v_mfma_f32_32x32x16_bf16 v[66:81], v[4:7], v[98:101], v[66:81]
	s_waitcnt lgkmcnt(3)
	v_mfma_f32_32x32x16_bf16 v[82:97], v[0:3], v[102:105], v[82:97]
	v_and_b32_e32 v1, 64, v208
	v_xor_b32_e32 v0, 32, v208
	v_add_u32_e32 v1, 64, v1
	v_cmp_lt_i32_e64 s[4:5], v0, v1
	s_nop 1
	s_nop 0
	v_cndmask_b32_e64 v0, v208, v0, s[4:5]
	s_waitcnt lgkmcnt(2)
	v_mfma_f32_32x32x16_bf16 v[66:81], v[8:11], v[102:105], v[66:81]
	v_lshlrev_b32_e32 v181, 2, v0
	s_waitcnt lgkmcnt(0)
	v_mfma_f32_32x32x16_bf16 v[82:97], v[16:19], v[110:113], v[82:97]
	v_mfma_f32_32x32x16_bf16 v[66:81], v[12:15], v[110:113], v[66:81]
	s_nop 10
	v_mul_f32_e64 v1, |v82|, s76
	v_mul_f32_e64 v3, |v83|, s76
	v_mul_f32_e64 v17, |v84|, s76
	v_mul_f32_e64 v19, |v85|, s76
	v_mul_f32_e64 v21, |v86|, s76
	v_mul_f32_e64 v23, |v87|, s76
	v_mul_f32_e64 v25, |v88|, s76
	v_mul_f32_e64 v27, |v89|, s76
	v_mul_f32_e64 v29, |v90|, s76
	v_mul_f32_e64 v4, |v91|, s76
	v_mul_f32_e64 v6, |v92|, s76
	v_mul_f32_e64 v31, |v93|, s76
	v_mul_f32_e64 v147, |v94|, s76
	v_mul_f32_e64 v9, |v95|, s76
	v_mul_f32_e64 v11, |v96|, s76
	v_mul_f32_e64 v151, |v97|, s76
	v_mul_f32_e64 v13, |v66|, s76
	v_mul_f32_e64 v15, |v67|, s76
	v_mul_f32_e64 v155, |v68|, s76
	v_exp_f32_e32 v243, v1
	v_exp_f32_e32 v239, v3
	v_exp_f32_e32 v205, v17
	v_exp_f32_e32 v202, v19
	v_exp_f32_e32 v201, v21
	v_exp_f32_e32 v200, v23
	v_exp_f32_e32 v199, v25
	v_exp_f32_e32 v198, v27
	v_exp_f32_e32 v197, v29
	v_exp_f32_e32 v196, v4
	v_exp_f32_e32 v195, v6
	v_exp_f32_e32 v194, v31
	v_exp_f32_e32 v193, v147
	v_exp_f32_e32 v192, v9
	v_exp_f32_e32 v191, v11
	v_exp_f32_e32 v190, v151
	v_exp_f32_e32 v189, v13
	v_exp_f32_e32 v187, v15
	v_exp_f32_e32 v186, v155
	v_max_f32_e32 v0, v82, v82
	v_max_f32_e32 v2, v83, v83
	v_max_f32_e32 v16, v84, v84
	v_max_f32_e32 v18, v85, v85
	v_max_f32_e32 v20, v86, v86
	v_max_f32_e32 v22, v87, v87
	v_max_f32_e32 v24, v88, v88
	v_max_f32_e32 v26, v89, v89
	v_max_f32_e32 v28, v90, v90
	v_max_f32_e32 v30, v91, v91
	v_max_f32_e32 v5, v92, v92
	v_max_f32_e32 v7, v93, v93
	v_max_f32_e32 v145, v94, v94
	v_max_f32_e32 v8, v95, v95
	v_max_f32_e32 v10, v96, v96
	v_max_f32_e32 v149, v97, v97
	v_max_f32_e32 v12, v66, v66
	v_max_f32_e32 v14, v67, v67
	v_max_f32_e32 v153, v68, v68
	v_max_f32_e32 v160, 0, v0
	v_max_f32_e32 v158, 0, v2
	v_max_f32_e32 v156, 0, v16
	v_max_f32_e32 v154, 0, v18
	v_max_f32_e32 v152, 0, v20
	v_max_f32_e32 v150, 0, v22
	v_max_f32_e32 v148, 0, v24
	v_max_f32_e32 v146, 0, v26
	v_max_f32_e32 v172, 0, v28
	v_max_f32_e32 v170, 0, v30
	v_max_f32_e32 v173, 0, v5
	v_max_f32_e32 v171, 0, v7
	v_max_f32_e32 v168, 0, v145
	v_max_f32_e32 v166, 0, v8
	v_max_f32_e32 v169, 0, v10
	v_max_f32_e32 v167, 0, v149
	v_max_f32_e32 v162, 0, v12
	v_max_f32_e32 v164, 0, v14
	v_max_f32_e32 v163, 0, v153
	v_max_f32_e32 v165, v69, v69
	v_mul_f32_e64 v185, |v69|, s76
	v_max_f32_e32 v161, v70, v70
	v_mul_f32_e64 v184, |v70|, s76
	v_max_f32_e32 v159, v71, v71
	v_mul_f32_e64 v183, |v71|, s76
	v_max_f32_e32 v157, v72, v72
	v_mul_f32_e64 v182, |v72|, s76
	v_max_f32_e32 v155, v73, v73
	v_mul_f32_e64 v153, |v73|, s76
	v_max_f32_e32 v151, v74, v74
	v_mul_f32_e64 v149, |v74|, s76
	v_max_f32_e32 v147, v75, v75
	v_mul_f32_e64 v145, |v75|, s76
	s_and_saveexec_b64 s[4:5], s[0:1]
	s_xor_b64 s[38:39], exec, s[4:5]
	s_cbranch_execz .LBB0_280
	v_add_f32_e32 v0, 1.0, v243
	v_add_f32_e32 v2, 1.0, v239
	v_log_f32_e32 v0, v0
	v_log_f32_e32 v2, v2
	v_mul_f32_e32 v1, 0x3f317217, v0
	v_fma_f32 v1, v0, s77, -v1
	v_fmac_f32_e32 v1, 0x3377d1cf, v0
	v_fmac_f32_e32 v1, 0x3f317217, v0
	v_add_f32_e32 v3, 1.0, v205
	v_add_u32_e32 v22, s42, v176
	v_mov_b32_e32 v0, v1
	v_mul_f32_e32 v1, 0x3f317217, v2
	v_fma_f32 v1, v2, s77, -v1
	v_fmac_f32_e32 v1, 0x3377d1cf, v2
	v_log_f32_e32 v3, v3
	v_fmac_f32_e32 v1, 0x3f317217, v2
	v_add_f32_e32 v4, 1.0, v202
	v_subrev_u32_e32 v15, 63, v22
	v_mov_b32_e32 v2, v1
	v_mul_f32_e32 v1, 0x3f317217, v3
	v_fma_f32 v1, v3, s77, -v1
	v_log_f32_e32 v5, v4
	v_fmac_f32_e32 v1, 0x3377d1cf, v3
	v_fmac_f32_e32 v1, 0x3f317217, v3
	v_max_f32_e32 v161, 0, v161
	v_max_f32_e32 v159, 0, v159
	v_mov_b32_e32 v4, v1
	v_mul_f32_e32 v1, 0x3f317217, v5
	v_add_f32_e32 v3, 1.0, v201
	v_fma_f32 v1, v5, s77, -v1
	v_fmac_f32_e32 v1, 0x3377d1cf, v5
	v_fmac_f32_e32 v1, 0x3f317217, v5
	v_log_f32_e32 v3, v3
	v_max_f32_e32 v157, 0, v157
	v_mov_b32_e32 v6, v1
	v_add_f32_e32 v5, 1.0, v200
	v_mul_f32_e32 v1, 0x3f317217, v3
	v_fma_f32 v1, v3, s77, -v1
	v_log_f32_e32 v5, v5
	v_fmac_f32_e32 v1, 0x3377d1cf, v3
	v_fmac_f32_e32 v1, 0x3f317217, v3
	v_max_f32_e32 v155, 0, v155
	v_mov_b32_e32 v8, v1
	v_mul_f32_e32 v1, 0x3f317217, v5
	v_add_f32_e32 v3, 1.0, v199
	v_fma_f32 v1, v5, s77, -v1
	v_fmac_f32_e32 v1, 0x3377d1cf, v5
	v_fmac_f32_e32 v1, 0x3f317217, v5
	v_log_f32_e32 v3, v3
	v_mov_b32_e32 v10, v1
	v_add_f32_e32 v5, 1.0, v198
	v_mul_f32_e32 v1, 0x3f317217, v3
	v_fma_f32 v1, v3, s77, -v1
	v_log_f32_e32 v5, v5
	v_fmac_f32_e32 v1, 0x3377d1cf, v3
; DI int crow(int i, int h) { return (i & 3) + 8 * (i >> 2) + 4 * h; }
; DI float shx32(float v) { return __shfl_xor(v, 32); }
; template <bool MASKED>
; DI void sb_weights(f32x16 (&Sx)[2], float& carry, int kt, int t, int h) {
;     ...
;         float L[16];
; #pragma unroll
;         for (int i = 0; i < 16; ++i) {
;           const float z = Sx[mt][i];
;           const bool ok = !MASKED || (kt * 64 + mt * 32 + crow(i, h) < t);
;           const float sp = fmaxf(z, 0.f) + __logf(1.f + __expf(-fabsf(z)));
;           L[i] = ok ? -sp : 0.f;
;           Sx[mt][i] = ok ? (z - sp) : NEG;
;         }
;         float G[4], Go[4];
; #pragma unroll
;         for (int gg = 0; gg < 4; ++gg) { G[gg] = (L[4 * gg] + L[4 * gg + 1]) + (L[4 * gg + 2] + L[4 * gg + 3]); Go[gg] = shx32(G[gg]); }
;         float T[4];
;         T[3] = 0.f; T[2] = G[3] + Go[3]; T[1] = T[2] + (G[2] + Go[2]); T[0] = T[1] + (G[1] + Go[1]);
	v_fmac_f32_e32 v1, 0x3f317217, v3
	v_mov_b32_e32 v16, v1
	v_mul_f32_e32 v1, 0x3f317217, v5
	v_fma_f32 v1, v5, s77, -v1
	v_fmac_f32_e32 v1, 0x3377d1cf, v5
	v_fmac_f32_e32 v1, 0x3f317217, v5
	v_add_f32_e32 v3, 1.0, v197
	v_log_f32_e32 v3, v3
	v_mov_b32_e32 v18, v1
	v_add_u32_e32 v1, -15, v22
	v_mul_f32_e32 v5, 0x3f317217, v3
	v_fma_f32 v5, v3, s77, -v5
	v_fmac_f32_e32 v5, 0x3377d1cf, v3
	v_fmac_f32_e32 v5, 0x3f317217, v3
	v_mov_b32_e32 v3, v5
	v_add_f32_e32 v5, 1.0, v196
	v_add_f32_e32 v3, v172, v3
	v_cmp_lt_i32_e64 s[0:1], v1, v130
	v_log_f32_e32 v5, v5
	s_nop 0
	v_cndmask_b32_e64 v1, 0, -v3, s[0:1]
	v_sub_f32_e32 v3, v90, v3
	v_cndmask_b32_e64 v24, v214, v3, s[0:1]
	v_mul_f32_e32 v7, 0x3f317217, v5
	v_fma_f32 v7, v5, s77, -v7
	v_fmac_f32_e32 v7, 0x3377d1cf, v5
	v_add_u32_e32 v3, -14, v22
	v_fmac_f32_e32 v7, 0x3f317217, v5
	v_cmp_lt_i32_e64 s[0:1], v3, v130
	v_add_f32_e32 v3, 1.0, v195
	v_mov_b32_e32 v5, v7
	v_add_f32_e32 v5, v170, v5
	v_log_f32_e32 v3, v3
	v_cndmask_b32_e64 v25, 0, -v5, s[0:1]
	v_sub_f32_e32 v5, v91, v5
	v_cndmask_b32_e64 v90, v214, v5, s[0:1]
	v_mul_f32_e32 v7, 0x3f317217, v3
	v_fma_f32 v7, v3, s77, -v7
	v_fmac_f32_e32 v7, 0x3377d1cf, v3
	v_add_u32_e32 v5, -13, v22
	v_fmac_f32_e32 v7, 0x3f317217, v3
	v_add_f32_e32 v20, v1, v25
	v_cmp_lt_i32_e64 s[0:1], v5, v130
	v_add_f32_e32 v5, 1.0, v194
	v_mov_b32_e32 v3, v7
	v_add_f32_e32 v3, v173, v3
	v_log_f32_e32 v5, v5
	v_cndmask_b32_e64 v26, 0, -v3, s[0:1]
	v_sub_f32_e32 v3, v92, v3
	v_cndmask_b32_e64 v91, v214, v3, s[0:1]
	v_mul_f32_e32 v7, 0x3f317217, v5
	v_fma_f32 v7, v5, s77, -v7
	v_fmac_f32_e32 v7, 0x3377d1cf, v5
	v_add_u32_e32 v3, -12, v22
	v_fmac_f32_e32 v7, 0x3f317217, v5
	v_cmp_lt_i32_e64 s[0:1], v3, v130
	v_add_f32_e32 v3, 1.0, v193
	v_mov_b32_e32 v5, v7
	v_add_f32_e32 v5, v171, v5
	v_log_f32_e32 v3, v3
	v_cndmask_b32_e64 v27, 0, -v5, s[0:1]
	v_sub_f32_e32 v5, v93, v5
	v_cndmask_b32_e64 v92, v214, v5, s[0:1]
	v_mul_f32_e32 v7, 0x3f317217, v3
	v_fma_f32 v7, v3, s77, -v7
	v_fmac_f32_e32 v7, 0x3377d1cf, v3
	v_fmac_f32_e32 v7, 0x3f317217, v3
	v_add_u32_e32 v5, -7, v22
	v_mov_b32_e32 v3, v7
	v_add_f32_e32 v7, 1.0, v192
	v_add_f32_e32 v3, v168, v3
	v_cmp_lt_i32_e64 s[0:1], v5, v130
	v_log_f32_e32 v7, v7
	s_nop 0
	v_cndmask_b32_e64 v5, 0, -v3, s[0:1]
	v_sub_f32_e32 v3, v94, v3
	v_cndmask_b32_e64 v3, v214, v3, s[0:1]
	v_mul_f32_e32 v11, 0x3f317217, v7
	v_fma_f32 v11, v7, s77, -v11
	v_fmac_f32_e32 v11, 0x3377d1cf, v7
	v_fmac_f32_e32 v11, 0x3f317217, v7
	v_add_u32_e32 v9, -6, v22
	v_mov_b32_e32 v7, v11
	v_add_f32_e32 v11, 1.0, v191
	v_add_f32_e32 v7, v166, v7
	v_cmp_lt_i32_e64 s[0:1], v9, v130
	v_log_f32_e32 v11, v11
	s_nop 0
	v_cndmask_b32_e64 v9, 0, -v7, s[0:1]
	v_sub_f32_e32 v7, v95, v7
	v_cndmask_b32_e64 v7, v214, v7, s[0:1]
	v_mul_f32_e32 v13, 0x3f317217, v11
	v_fma_f32 v13, v11, s77, -v13
	v_fmac_f32_e32 v13, 0x3377d1cf, v11
	v_add_u32_e32 v12, -5, v22
	v_fmac_f32_e32 v13, 0x3f317217, v11
	v_add_f32_e32 v5, v5, v9
	v_cmp_lt_i32_e64 s[0:1], v12, v130
	v_add_f32_e32 v12, 1.0, v190
	v_mov_b32_e32 v11, v13
	v_add_f32_e32 v11, v169, v11
	v_log_f32_e32 v12, v12
	v_cndmask_b32_e64 v13, 0, -v11, s[0:1]
	v_sub_f32_e32 v11, v96, v11
	v_cndmask_b32_e64 v11, v214, v11, s[0:1]
	v_mul_f32_e32 v17, 0x3f317217, v12
	v_fma_f32 v17, v12, s77, -v17
	v_fmac_f32_e32 v17, 0x3377d1cf, v12
	v_fmac_f32_e32 v17, 0x3f317217, v12
	v_add_u32_e32 v14, -4, v22
	v_mov_b32_e32 v12, v17
	v_add_f32_e32 v12, v167, v12
	v_cmp_lt_i32_e64 s[0:1], v14, v130
	s_nop 1
	s_nop 0
	v_cndmask_b32_e64 v17, 0, -v12, s[0:1]
	v_add_f32_e32 v14, v13, v17
	v_add_f32_e32 v5, v5, v14
	ds_bpermute_b32 v19, v181, v5
	v_sub_f32_e32 v12, v97, v12
	v_cndmask_b32_e64 v21, v214, v12, s[0:1]
	v_max_f32_e32 v97, v78, v78
	v_max_f32_e32 v97, 0, v97
	s_waitcnt lgkmcnt(0)
	v_cndmask_b32_e32 v1, 0, v19, vcc
	v_add_f32_e32 v1, v188, v1
	v_add_f32_e32 v14, v5, v19
	v_add_f32_e32 v5, v17, v1
	v_add_f32_e32 v1, v21, v1
	v_mul_f32_e32 v1, 0x3fb8aa3b, v1
	v_exp_f32_e32 v31, v1
	v_add_f32_e32 v1, v11, v5
	v_add_f32_e32 v13, v13, v5
	v_mul_f32_e32 v1, 0x3fb8aa3b, v1
	v_exp_f32_e32 v30, v1
	v_add_f32_e32 v1, v7, v13
	v_mul_f32_e32 v1, 0x3fb8aa3b, v1
	v_exp_f32_e32 v29, v1
	v_add_f32_e32 v1, 1.0, v189
	v_add_f32_e32 v9, v9, v13
	v_add_f32_e32 v3, v3, v9
	v_log_f32_e32 v1, v1
	v_mul_f32_e32 v3, 0x3fb8aa3b, v3
	v_exp_f32_e32 v28, v3
	v_exp_f32_e32 v9, v153
	v_mul_f32_e32 v3, 0x3f317217, v1
	v_fma_f32 v3, v1, s77, -v3
	v_fmac_f32_e32 v3, 0x3377d1cf, v1
	v_fmac_f32_e32 v3, 0x3f317217, v1
	v_exp_f32_e32 v11, v149
	v_exp_f32_e32 v13, v145
	v_mov_b32_e32 v1, v3
	v_add_f32_e32 v3, 1.0, v187
	v_add_f32_e32 v1, v162, v1
	v_cmp_lt_i32_e64 s[0:1], v15, v130
	v_log_f32_e32 v3, v3
	s_nop 0
	v_cndmask_b32_e64 v23, 0, -v1, s[0:1]
	v_sub_f32_e32 v1, v66, v1
	v_cndmask_b32_e64 v66, v214, v1, s[0:1]
	v_mul_f32_e32 v5, 0x3f317217, v3
	v_fma_f32 v5, v3, s77, -v5
	v_fmac_f32_e32 v5, 0x3377d1cf, v3
	v_subrev_u32_e32 v1, 62, v22
	v_fmac_f32_e32 v5, 0x3f317217, v3
	v_mul_f32_e64 v17, |v76|, s76
	v_exp_f32_e32 v17, v17
	v_cmp_lt_i32_e64 s[0:1], v1, v130
	v_add_f32_e32 v1, 1.0, v186
	v_mov_b32_e32 v3, v5
	v_add_f32_e32 v3, v164, v3
	v_log_f32_e32 v1, v1
	v_cndmask_b32_e64 v94, 0, -v3, s[0:1]
	v_sub_f32_e32 v3, v67, v3
	v_cndmask_b32_e64 v67, v214, v3, s[0:1]
	v_mul_f32_e32 v5, 0x3f317217, v1
	v_fma_f32 v5, v1, s77, -v5
	v_fmac_f32_e32 v5, 0x3377d1cf, v1
	v_fmac_f32_e32 v5, 0x3f317217, v1
	v_subrev_u32_e32 v3, 61, v22
	v_add_f32_e32 v17, 1.0, v17
	v_mov_b32_e32 v1, v5
	v_exp_f32_e32 v5, v185
	v_cmp_lt_i32_e64 s[0:1], v3, v130
	v_add_f32_e32 v1, v163, v1
	v_max_f32_e32 v153, 0, v151
	v_add_f32_e32 v3, 1.0, v5
	v_cndmask_b32_e64 v95, 0, -v1, s[0:1]
	v_sub_f32_e32 v1, v68, v1
; DI int crow(int i, int h) { return (i & 3) + 8 * (i >> 2) + 4 * h; }
; DI float shx32(float v) { return __shfl_xor(v, 32); }
; template <bool MASKED>
; DI void sb_weights(f32x16 (&Sx)[2], float& carry, int kt, int t, int h) {
;     ...
;         float L[16];
; #pragma unroll
;         for (int i = 0; i < 16; ++i) {
;           const float z = Sx[mt][i];
;           const bool ok = !MASKED || (kt * 64 + mt * 32 + crow(i, h) < t);
;           const float sp = fmaxf(z, 0.f) + __logf(1.f + __expf(-fabsf(z)));
;           L[i] = ok ? -sp : 0.f;
;           Sx[mt][i] = ok ? (z - sp) : NEG;
;         }
;         float G[4], Go[4];
; #pragma unroll
;         for (int gg = 0; gg < 4; ++gg) { G[gg] = (L[4 * gg] + L[4 * gg + 1]) + (L[4 * gg + 2] + L[4 * gg + 3]); Go[gg] = shx32(G[gg]); }
;         float T[4];
;         T[3] = 0.f; T[2] = G[3] + Go[3]; T[1] = T[2] + (G[2] + Go[2]); T[0] = T[1] + (G[1] + Go[1]);
	v_log_f32_e32 v3, v3
	v_cndmask_b32_e64 v68, v214, v1, s[0:1]
	v_subrev_u32_e32 v1, 60, v22
	v_max_f32_e32 v5, 0, v165
	v_mul_f32_e32 v7, 0x3f317217, v3
	v_fma_f32 v7, v3, s77, -v7
	v_fmac_f32_e32 v7, 0x3377d1cf, v3
	v_fmac_f32_e32 v7, 0x3f317217, v3
	v_max_f32_e32 v151, 0, v147
	v_add_f32_e32 v23, v23, v94
	v_mov_b32_e32 v3, v7
	v_exp_f32_e32 v7, v184
	v_cmp_lt_i32_e64 s[0:1], v1, v130
	v_add_f32_e32 v3, v5, v3
	v_add_f32_e32 v12, v26, v27
	v_add_f32_e32 v1, 1.0, v7
	v_cndmask_b32_e64 v96, 0, -v3, s[0:1]
	v_sub_f32_e32 v3, v69, v3
	v_log_f32_e32 v1, v1
	v_cndmask_b32_e64 v69, v214, v3, s[0:1]
	v_exp_f32_e32 v5, v183
	v_exp_f32_e32 v7, v182
	v_mul_f32_e32 v3, 0x3f317217, v1
	v_fma_f32 v3, v1, s77, -v3
	v_fmac_f32_e32 v3, 0x3377d1cf, v1
	v_fmac_f32_e32 v3, 0x3f317217, v1
	v_add_f32_e32 v93, v144, v14
	v_mov_b32_e32 v1, v3
	v_add_f32_e32 v3, 1.0, v5
	v_log_f32_e32 v3, v3
	v_mov_b32_e32 v1, v1
	v_pk_add_f32 v[0:1], v[160:161], v[0:1]
	v_mul_f32_e32 v5, 0x3f317217, v3
	v_fma_f32 v5, v3, s77, -v5
	v_fmac_f32_e32 v5, 0x3377d1cf, v3
	v_fmac_f32_e32 v5, 0x3f317217, v3
	v_mov_b32_e32 v3, v5
	v_add_f32_e32 v5, 1.0, v7
	v_log_f32_e32 v5, v5
	v_mov_b32_e32 v3, v3
	v_pk_add_f32 v[2:3], v[158:159], v[2:3]
	v_mul_f32_e32 v7, 0x3f317217, v5
	v_fma_f32 v7, v5, s77, -v7
	v_fmac_f32_e32 v7, 0x3377d1cf, v5
	v_fmac_f32_e32 v7, 0x3f317217, v5
	v_mov_b32_e32 v5, v7
	v_add_f32_e32 v7, 1.0, v9
	v_log_f32_e32 v7, v7
	v_mov_b32_e32 v5, v5
	v_pk_add_f32 v[4:5], v[156:157], v[4:5]
	v_mul_f32_e32 v9, 0x3f317217, v7
	v_fma_f32 v9, v7, s77, -v9
	v_fmac_f32_e32 v9, 0x3377d1cf, v7
	v_fmac_f32_e32 v9, 0x3f317217, v7
	v_or_b32_e32 v156, 10, v15
	v_mov_b32_e32 v7, v9
	v_add_f32_e32 v9, 1.0, v11
	v_log_f32_e32 v9, v9
	v_mov_b32_e32 v7, v7
	v_pk_add_f32 v[6:7], v[154:155], v[6:7]
	v_mul_f32_e32 v11, 0x3f317217, v9
	v_fma_f32 v11, v9, s77, -v11
	v_fmac_f32_e32 v11, 0x3377d1cf, v9
	v_fmac_f32_e32 v11, 0x3f317217, v9
	v_or_b32_e32 v154, 11, v15
	v_mov_b32_e32 v9, v11
	v_add_f32_e32 v11, 1.0, v13
	v_log_f32_e32 v11, v11
	v_mov_b32_e32 v9, v9
	v_pk_add_f32 v[8:9], v[152:153], v[8:9]
	v_mul_f32_e32 v13, 0x3f317217, v11
	v_fma_f32 v13, v11, s77, -v13
	v_fmac_f32_e32 v13, 0x3377d1cf, v11
	v_fmac_f32_e32 v13, 0x3f317217, v11
	v_or_b32_e32 v152, 16, v15
	v_mov_b32_e32 v11, v13
	v_max_f32_e32 v13, v76, v76
	v_log_f32_e32 v17, v17
	v_mul_f32_e64 v19, |v77|, s76
	v_exp_f32_e32 v19, v19
	v_max_f32_e32 v149, 0, v13
	v_mul_f32_e32 v13, 0x3f317217, v17
	v_fma_f32 v13, v17, s77, -v13
	v_fmac_f32_e32 v13, 0x3377d1cf, v17
	v_fmac_f32_e32 v13, 0x3f317217, v17
	v_add_f32_e32 v19, 1.0, v19
	v_pk_add_f32 v[10:11], v[150:151], v[10:11]
	v_mov_b32_e32 v17, v13
	v_max_f32_e32 v13, v77, v77
	v_log_f32_e32 v19, v19
	v_max_f32_e32 v147, 0, v13
	v_mul_f32_e64 v21, |v78|, s76
	v_exp_f32_e32 v21, v21
	v_mul_f32_e32 v13, 0x3f317217, v19
	v_fma_f32 v13, v19, s77, -v13
	v_fmac_f32_e32 v13, 0x3377d1cf, v19
	v_fmac_f32_e32 v13, 0x3f317217, v19
	v_or_b32_e32 v150, 17, v15
	v_or_b32_e32 v151, 19, v15
	v_mov_b32_e32 v19, v13
	v_add_f32_e32 v13, 1.0, v21
	v_log_f32_e32 v13, v13
	v_subrev_u32_e32 v21, 39, v22
	v_mul_f32_e32 v145, 0x3f317217, v13
	v_fma_f32 v145, v13, s77, -v145
	v_fmac_f32_e32 v145, 0x3377d1cf, v13
	v_fmac_f32_e32 v145, 0x3f317217, v13
	v_mov_b32_e32 v13, v145
	v_add_f32_e32 v13, v97, v13
	v_mul_f32_e64 v97, |v79|, s76
	v_exp_f32_e32 v97, v97
	v_cmp_lt_i32_e64 s[0:1], v21, v130
	s_nop 1
	s_nop 0
	v_cndmask_b32_e64 v21, 0, -v13, s[0:1]
	v_sub_f32_e32 v13, v78, v13
	v_cndmask_b32_e64 v162, v214, v13, s[0:1]
	v_add_f32_e32 v13, 1.0, v97
	v_max_f32_e32 v97, v79, v79
	v_max_f32_e32 v97, 0, v97
	v_log_f32_e32 v13, v13
	v_subrev_u32_e32 v78, 38, v22
	v_mul_f32_e32 v145, 0x3f317217, v13
	v_fma_f32 v145, v13, s77, -v145
	v_fmac_f32_e32 v145, 0x3377d1cf, v13
	v_fmac_f32_e32 v145, 0x3f317217, v13
	v_mov_b32_e32 v13, v145
	v_add_f32_e32 v97, v97, v13
	v_mul_f32_e64 v13, |v80|, s76
	v_exp_f32_e32 v145, v13
	v_cmp_lt_i32_e64 s[0:1], v78, v130
	v_sub_f32_e32 v78, v79, v97
	s_nop 0
	v_cndmask_b32_e64 v13, 0, -v97, s[0:1]
	v_cndmask_b32_e64 v97, v214, v78, s[0:1]
	v_add_f32_e32 v78, 1.0, v145
	v_max_f32_e32 v145, v80, v80
	v_max_f32_e32 v145, 0, v145
	v_log_f32_e32 v78, v78
	v_subrev_u32_e32 v79, 37, v22
	v_subrev_u32_e32 v22, 36, v22
	v_pk_add_f32 v[20:21], v[20:21], v[12:13]
	v_mul_f32_e32 v163, 0x3f317217, v78
	v_fma_f32 v163, v78, s77, -v163
	v_fmac_f32_e32 v163, 0x3377d1cf, v78
	v_fmac_f32_e32 v163, 0x3f317217, v78
	v_mov_b32_e32 v78, v163
	v_add_f32_e32 v78, v145, v78
	v_mul_f32_e64 v145, |v81|, s76
	v_exp_f32_e32 v145, v145
	v_cmp_lt_i32_e64 s[0:1], v79, v130
	s_nop 1
	s_nop 0
	v_cndmask_b32_e64 v163, 0, -v78, s[0:1]
	v_sub_f32_e32 v78, v80, v78
	v_cndmask_b32_e64 v164, v214, v78, s[0:1]
	v_add_f32_e32 v78, 1.0, v145
	v_log_f32_e32 v78, v78
	v_max_f32_e32 v79, v81, v81
	v_max_f32_e32 v79, 0, v79
	v_mul_f32_e32 v80, 0x3f317217, v78
	v_fma_f32 v80, v78, s77, -v80
	v_fmac_f32_e32 v80, 0x3377d1cf, v78
	v_fmac_f32_e32 v80, 0x3f317217, v78
	v_mov_b32_e32 v78, v80
	v_add_f32_e32 v78, v79, v78
	v_add_f32_e32 v79, v95, v96
	v_add_f32_e32 v23, v23, v79
	ds_bpermute_b32 v80, v181, v23
	v_cmp_lt_i32_e64 s[0:1], v22, v130
	v_sub_f32_e32 v22, v81, v78
	s_waitcnt lgkmcnt(0)
; DI float shx32(float v) { return __shfl_xor(v, 32); }
; template <bool MASKED>
; DI void sb_weights(f32x16 (&Sx)[2], float& carry, int kt, int t, int h) {
;     ...
;         float G[4], Go[4];
; #pragma unroll
;         for (int gg = 0; gg < 4; ++gg) { G[gg] = (L[4 * gg] + L[4 * gg + 1]) + (L[4 * gg + 2] + L[4 * gg + 3]); Go[gg] = shx32(G[gg]); }
;         float T[4];
;         T[3] = 0.f; T[2] = G[3] + Go[3]; T[1] = T[2] + (G[2] + Go[2]); T[0] = T[1] + (G[1] + Go[1]);
;         const float tot = T[0] + (G[0] + Go[0]);
; #pragma unroll
;         for (int gg = 0; gg < 4; ++gg) {
;           const float s3 = carry + T[gg] + (h ? 0.f : Go[gg]);
;           const float s2 = s3 + L[4 * gg + 3], s1 = s2 + L[4 * gg + 2], s0 = s1 + L[4 * gg + 1];
;           Sx[mt][4 * gg + 3] = __expf(Sx[mt][4 * gg + 3] + s3);
;           Sx[mt][4 * gg + 2] = __expf(Sx[mt][4 * gg + 2] + s2);
;           Sx[mt][4 * gg + 1] = __expf(Sx[mt][4 * gg + 1] + s1);
;           Sx[mt][4 * gg + 0] = __expf(Sx[mt][4 * gg + 0] + s0);
;         }
;         carry += tot;
	v_add_f32_e32 v145, v23, v80
	v_cndmask_b32_e64 v165, 0, -v78, s[0:1]
	v_or_b32_e32 v78, 32, v15
	v_cndmask_b32_e64 v166, v214, v22, s[0:1]
	v_cndmask_b32_e32 v167, 0, v80, vcc
	v_sub_f32_e32 v22, v82, v0
	v_cmp_lt_i32_e64 s[4:5], v78, v130
	v_or_b32_e32 v80, 33, v15
	v_cmp_lt_i32_e64 s[6:7], v80, v130
	v_cndmask_b32_e64 v168, v214, v22, s[4:5]
	v_sub_f32_e32 v22, v83, v2
	v_or_b32_e32 v80, 34, v15
	v_cndmask_b32_e64 v169, v214, v22, s[6:7]
	v_sub_f32_e32 v22, v84, v4
	v_cmp_lt_i32_e64 s[8:9], v80, v130
	v_or_b32_e32 v80, 35, v15
	v_cmp_lt_i32_e64 s[10:11], v80, v130
	v_cndmask_b32_e64 v170, v214, v22, s[8:9]
	v_sub_f32_e32 v22, v85, v6
	v_or_b32_e32 v80, 40, v15
	v_cndmask_b32_e64 v171, v214, v22, s[10:11]
	v_sub_f32_e32 v22, v86, v8
	v_cmp_lt_i32_e64 s[12:13], v80, v130
	v_or_b32_e32 v80, 41, v15
	v_cmp_lt_i32_e64 s[14:15], v80, v130
	v_cndmask_b32_e64 v172, v214, v22, s[12:13]
	v_sub_f32_e32 v22, v87, v10
	v_pk_add_f32 v[80:81], v[148:149], v[16:17]
	v_or_b32_e32 v17, 42, v15
	v_or_b32_e32 v23, 8, v15
	v_or_b32_e32 v78, 9, v15
	v_cndmask_b32_e64 v173, v214, v22, s[14:15]
	v_sub_f32_e32 v16, v88, v80
	v_or_b32_e32 v22, 18, v15
	v_cmp_lt_i32_e64 s[16:17], v17, v130
	v_pk_add_f32 v[82:83], v[146:147], v[18:19]
	v_or_b32_e32 v15, 43, v15
	v_cndmask_b32_e64 v182, v214, v16, s[16:17]
	v_sub_f32_e32 v16, v89, v82
	v_cmp_lt_i32_e64 s[18:19], v15, v130
	v_cndmask_b32_e64 v88, 0, -v6, s[10:11]
	v_cmp_lt_i32_e64 s[10:11], v152, v131
	v_cndmask_b32_e64 v183, v214, v16, s[18:19]
	v_cndmask_b32_e64 v16, 0, -v0, s[4:5]
	v_cmp_lt_i32_e64 s[4:5], v78, v131
	ds_bpermute_b32 v78, v181, v20
	v_cndmask_b32_e64 v18, 0, -v8, s[12:13]
	v_cmp_lt_i32_e64 s[12:13], v150, v131
	v_cndmask_b32_e64 v146, 0, -v10, s[14:15]
	v_cmp_lt_i32_e64 s[14:15], v22, v131
	v_cndmask_b32_e64 v148, 0, -v80, s[16:17]
	v_cmp_lt_i32_e64 s[16:17], v151, v131
	v_cndmask_b32_e64 v19, 0, -v9, s[10:11]
	v_cndmask_b32_e64 v147, 0, -v11, s[12:13]
	v_cndmask_b32_e64 v149, 0, -v81, s[14:15]
	v_cndmask_b32_e64 v151, 0, -v83, s[16:17]
	v_cndmask_b32_e64 v150, 0, -v82, s[18:19]
	v_add_f32_e32 v79, v163, v165
	v_cmp_lt_i32_e64 s[0:1], v23, v131
	v_cndmask_b32_e64 v84, 0, -v2, s[6:7]
	v_cmp_lt_i32_e64 s[6:7], v156, v131
	v_cndmask_b32_e64 v86, 0, -v4, s[8:9]
	v_cmp_lt_i32_e64 s[8:9], v154, v131
	v_pk_add_f32 v[18:19], v[18:19], v[146:147]
	v_pk_add_f32 v[22:23], v[148:149], v[150:151]
	v_cndmask_b32_e64 v17, 0, -v1, s[0:1]
	v_cndmask_b32_e64 v85, 0, -v3, s[4:5]
	v_cndmask_b32_e64 v87, 0, -v5, s[6:7]
	v_cndmask_b32_e64 v89, 0, -v7, s[8:9]
	v_pk_add_f32 v[18:19], v[18:19], v[22:23]
	s_waitcnt lgkmcnt(0)
	v_pk_add_f32 v[20:21], v[20:21], v[78:79]
	v_pk_add_f32 v[16:17], v[16:17], v[84:85]
	ds_bpermute_b32 v152, v181, v18
	ds_bpermute_b32 v15, v181, v21
	ds_bpermute_b32 v153, v181, v19
	v_pk_add_f32 v[22:23], v[86:87], v[88:89]
	s_waitcnt lgkmcnt(1)
	v_pk_add_f32 v[158:159], v[20:21], v[14:15]
	v_pk_add_f32 v[154:155], v[16:17], v[22:23]
	ds_bpermute_b32 v156, v181, v154
	s_waitcnt lgkmcnt(1)
	v_pk_add_f32 v[16:17], v[18:19], v[152:153]
	ds_bpermute_b32 v157, v181, v155
	v_pk_add_f32 v[160:161], v[16:17], v[158:159]
	s_waitcnt lgkmcnt(1)
	v_cndmask_b32_e32 v2, 0, v156, vcc
	v_add_f32_e32 v0, v144, v160
	v_add_f32_e32 v0, v2, v0
	v_add_f32_e32 v2, v88, v0
	v_add_f32_e32 v0, v171, v0
	v_mul_f32_e32 v0, 0x3fb8aa3b, v0
	v_exp_f32_e32 v19, v0
	v_add_f32_e32 v0, v170, v2
	v_add_f32_e32 v4, v86, v2
	v_mul_f32_e32 v0, 0x3fb8aa3b, v0
	v_exp_f32_e32 v18, v0
	v_add_f32_e32 v0, v169, v4
	v_add_f32_e32 v6, v84, v4
	v_mul_f32_e32 v0, 0x3fb8aa3b, v0
	v_exp_f32_e32 v17, v0
	v_add_f32_e32 v0, v168, v6
	v_mul_f32_e32 v0, 0x3fb8aa3b, v0
	v_exp_f32_e32 v16, v0
	v_add_f32_e32 v0, v144, v158
	v_cndmask_b32_e32 v2, 0, v152, vcc
	v_add_f32_e32 v0, v2, v0
	v_add_f32_e32 v2, v150, v0
	v_add_f32_e32 v0, v183, v0
	v_mul_f32_e32 v0, 0x3fb8aa3b, v0
	v_exp_f32_e32 v23, v0
	v_add_f32_e32 v0, v182, v2
	v_add_f32_e32 v4, v148, v2
	v_mul_f32_e32 v0, 0x3fb8aa3b, v0
	v_exp_f32_e32 v22, v0
	v_add_f32_e32 v0, v173, v4
	v_add_f32_e32 v6, v146, v4
	v_mul_f32_e32 v0, 0x3fb8aa3b, v0
	v_exp_f32_e32 v21, v0
	v_add_f32_e32 v0, v172, v6
	v_mul_f32_e32 v0, 0x3fb8aa3b, v0
	v_exp_f32_e32 v20, v0
	v_cndmask_b32_e32 v0, 0, v78, vcc
	v_add_f32_e32 v0, v0, v93
	v_add_f32_e32 v2, v27, v0
	v_add_f32_e32 v0, v92, v0
	v_mul_f32_e32 v0, 0x3fb8aa3b, v0
	v_exp_f32_e32 v27, v0
	v_add_f32_e32 v0, v91, v2
	v_add_f32_e32 v4, v26, v2
	v_mul_f32_e32 v0, 0x3fb8aa3b, v0
	v_exp_f32_e32 v26, v0
	v_add_f32_e32 v0, v90, v4
	v_add_f32_e32 v6, v25, v4
	v_mul_f32_e32 v0, 0x3fb8aa3b, v0
	v_exp_f32_e32 v25, v0
	v_add_f32_e32 v0, v24, v6
	v_mul_f32_e32 v0, 0x3fb8aa3b, v0
	v_exp_f32_e32 v24, v0
	v_sub_f32_e32 v0, v70, v1
	v_cndmask_b32_e64 v4, v214, v0, s[0:1]
	v_sub_f32_e32 v0, v71, v3
	v_cndmask_b32_e64 v8, v214, v0, s[4:5]
	v_sub_f32_e32 v0, v72, v5
	v_cndmask_b32_e64 v5, v214, v0, s[6:7]
	v_sub_f32_e32 v0, v73, v7
	v_cndmask_b32_e64 v6, v214, v0, s[8:9]
	v_sub_f32_e32 v0, v74, v9
	v_cndmask_b32_e64 v12, v214, v0, s[10:11]
	v_sub_f32_e32 v0, v75, v11
	v_cndmask_b32_e64 v9, v214, v0, s[12:13]
	v_sub_f32_e32 v0, v76, v81
	v_cndmask_b32_e64 v10, v214, v0, s[14:15]
	v_sub_f32_e32 v0, v77, v83
	v_cndmask_b32_e64 v11, v214, v0, s[16:17]
	s_waitcnt lgkmcnt(0)
; DI int crow(int i, int h) { return (i & 3) + 8 * (i >> 2) + 4 * h; }
; DI float shx32(float v) { return __shfl_xor(v, 32); }
; template <bool MASKED>
; DI void sb_weights(f32x16 (&Sx)[2], float& carry, int kt, int t, int h) {
; #pragma unroll
;     ...
;         float L[16];
; #pragma unroll
;         for (int i = 0; i < 16; ++i) {
;           const float z = Sx[mt][i];
;           const bool ok = !MASKED || (kt * 64 + mt * 32 + crow(i, h) < t);
;           const float sp = fmaxf(z, 0.f) + __logf(1.f + __expf(-fabsf(z)));
;           L[i] = ok ? -sp : 0.f;
;           Sx[mt][i] = ok ? (z - sp) : NEG;
;         }
;         float G[4], Go[4];
; #pragma unroll
;         for (int gg = 0; gg < 4; ++gg) { G[gg] = (L[4 * gg] + L[4 * gg + 1]) + (L[4 * gg + 2] + L[4 * gg + 3]); Go[gg] = shx32(G[gg]); }
;         float T[4];
;         T[3] = 0.f; T[2] = G[3] + Go[3]; T[1] = T[2] + (G[2] + Go[2]); T[0] = T[1] + (G[1] + Go[1]);
;         const float tot = T[0] + (G[0] + Go[0]);
; #pragma unroll
;         for (int gg = 0; gg < 4; ++gg) {
;           const float s3 = carry + T[gg] + (h ? 0.f : Go[gg]);
;           const float s2 = s3 + L[4 * gg + 3], s1 = s2 + L[4 * gg + 2], s0 = s1 + L[4 * gg + 1];
;           Sx[mt][4 * gg + 3] = __expf(Sx[mt][4 * gg + 3] + s3);
;           Sx[mt][4 * gg + 2] = __expf(Sx[mt][4 * gg + 2] + s2);
;           Sx[mt][4 * gg + 1] = __expf(Sx[mt][4 * gg + 1] + s1);
;           Sx[mt][4 * gg + 0] = __expf(Sx[mt][4 * gg + 0] + s0);
;         }
;         carry += tot;
;       }
; }
	v_pk_add_f32 v[0:1], v[154:155], v[156:157]
	s_nop 0
	v_pk_add_f32 v[0:1], v[0:1], v[160:161]
	s_nop 0
	v_pk_add_f32 v[70:71], v[144:145], v[0:1]
	s_nop 0
	v_add_f32_e32 v0, v70, v1
	v_add_f32_e32 v0, v167, v0
	v_add_f32_e32 v1, v96, v0
	v_add_f32_e32 v0, v69, v0
	v_mul_f32_e32 v0, 0x3fb8aa3b, v0
	v_exp_f32_e32 v3, v0
	v_add_f32_e32 v0, v68, v1
	v_add_f32_e32 v7, v95, v1
	v_mul_f32_e32 v0, 0x3fb8aa3b, v0
	v_exp_f32_e32 v2, v0
	v_add_f32_e32 v0, v67, v7
	v_add_f32_e32 v14, v94, v7
	v_mul_f32_e32 v0, 0x3fb8aa3b, v0
	v_exp_f32_e32 v1, v0
	v_add_f32_e32 v0, v66, v14
	v_add_f32_e32 v7, v70, v161
	v_cndmask_b32_e32 v14, 0, v157, vcc
	v_add_f32_e32 v7, v14, v7
	v_add_f32_e32 v14, v89, v7
	v_add_f32_e32 v6, v6, v7
	v_add_f32_e32 v5, v5, v14
	v_add_f32_e32 v66, v87, v14
	v_mul_f32_e32 v6, 0x3fb8aa3b, v6
	v_mul_f32_e32 v5, 0x3fb8aa3b, v5
	v_exp_f32_e32 v7, v6
	v_exp_f32_e32 v6, v5
	v_add_f32_e32 v5, v8, v66
	v_add_f32_e32 v8, v159, v70
	v_cndmask_b32_e32 v14, 0, v153, vcc
	v_add_f32_e32 v8, v14, v8
	v_add_f32_e32 v14, v151, v8
	v_add_f32_e32 v8, v11, v8
	v_mul_f32_e32 v8, 0x3fb8aa3b, v8
	v_exp_f32_e32 v11, v8
	v_add_f32_e32 v8, v10, v14
	v_add_f32_e32 v67, v85, v66
	v_add_f32_e32 v66, v149, v14
	v_mul_f32_e32 v8, 0x3fb8aa3b, v8
	v_exp_f32_e32 v10, v8
	v_add_f32_e32 v8, v9, v66
	v_add_f32_e32 v4, v4, v67
	v_add_f32_e32 v67, v147, v66
	v_mul_f32_e32 v8, 0x3fb8aa3b, v8
	v_exp_f32_e32 v9, v8
	v_add_f32_e32 v8, v12, v67
	v_add_f32_e32 v12, 0, v70
	v_cndmask_b32_e32 v14, 0, v15, vcc
	v_add_f32_e32 v12, v14, v12
	v_add_f32_e32 v14, v165, v12
	v_add_f32_e32 v12, v166, v12
	v_mul_f32_e32 v12, 0x3fb8aa3b, v12
	v_exp_f32_e32 v15, v12
	v_add_f32_e32 v12, v164, v14
	v_add_f32_e32 v66, v163, v14
	v_mul_f32_e32 v12, 0x3fb8aa3b, v12
	v_exp_f32_e32 v14, v12
	v_add_f32_e32 v12, v97, v66
	v_add_f32_e32 v67, v13, v66
	v_mul_f32_e32 v12, 0x3fb8aa3b, v12
	v_exp_f32_e32 v13, v12
	v_add_f32_e32 v12, v162, v67
	v_mul_f32_e32 v0, 0x3fb8aa3b, v0
	v_mul_f32_e32 v5, 0x3fb8aa3b, v5
	v_mul_f32_e32 v4, 0x3fb8aa3b, v4
	v_mul_f32_e32 v8, 0x3fb8aa3b, v8
	v_mul_f32_e32 v12, 0x3fb8aa3b, v12
	v_exp_f32_e32 v0, v0
	v_exp_f32_e32 v5, v5
	v_exp_f32_e32 v4, v4
	v_exp_f32_e32 v8, v8
	v_exp_f32_e32 v12, v12
	v_add_f32_e32 v144, v70, v71
.LBB0_280:
	s_andn2_saveexec_b64 s[6:7], s[38:39]
	s_cbranch_execz .LBB0_282
	v_add_f32_e32 v0, 1.0, v243
	v_mov_b32_e32 v30, v91
	v_max_f32_e32 v165, 0, v165
	v_log_f32_e32 v0, v0
	v_max_f32_e32 v161, 0, v161
	v_max_f32_e32 v159, 0, v159
	v_max_f32_e32 v157, 0, v157
	v_mul_f32_e32 v1, 0x3f317217, v0
	v_fma_f32 v1, v0, s77, -v1
	v_fmac_f32_e32 v1, 0x3377d1cf, v0
	v_fmac_f32_e32 v1, 0x3f317217, v0
	v_max_f32_e32 v155, 0, v155
	v_mov_b32_e32 v0, v1
	v_add_f32_e32 v1, 1.0, v239
	v_log_f32_e32 v1, v1
	s_nop 0
	v_mul_f32_e32 v2, 0x3f317217, v1
	v_fma_f32 v2, v1, s77, -v2
	v_fmac_f32_e32 v2, 0x3377d1cf, v1
	v_fmac_f32_e32 v2, 0x3f317217, v1
	v_add_f32_e32 v1, 1.0, v205
	v_log_f32_e32 v1, v1
	s_nop 0
	v_mul_f32_e32 v3, 0x3f317217, v1
	v_fma_f32 v3, v1, s77, -v3
	v_fmac_f32_e32 v3, 0x3377d1cf, v1
	v_fmac_f32_e32 v3, 0x3f317217, v1
	v_mov_b32_e32 v4, v3
	v_add_f32_e32 v1, 1.0, v202
	v_log_f32_e32 v1, v1
	s_nop 0
	v_mul_f32_e32 v3, 0x3f317217, v1
	v_fma_f32 v3, v1, s77, -v3
	v_fmac_f32_e32 v3, 0x3377d1cf, v1
	v_fmac_f32_e32 v3, 0x3f317217, v1
	v_mov_b32_e32 v6, v3
	v_add_f32_e32 v1, 1.0, v201
	v_log_f32_e32 v1, v1
	s_nop 0
	v_mul_f32_e32 v3, 0x3f317217, v1
	v_fma_f32 v3, v1, s77, -v3
	v_fmac_f32_e32 v3, 0x3377d1cf, v1
	v_fmac_f32_e32 v3, 0x3f317217, v1
	v_mov_b32_e32 v8, v3
	v_add_f32_e32 v1, 1.0, v200
	v_log_f32_e32 v1, v1
	s_nop 0
	v_mul_f32_e32 v3, 0x3f317217, v1
	v_fma_f32 v3, v1, s77, -v3
	v_fmac_f32_e32 v3, 0x3377d1cf, v1
	v_fmac_f32_e32 v3, 0x3f317217, v1
	v_mov_b32_e32 v10, v3
	v_add_f32_e32 v1, 1.0, v199
	v_log_f32_e32 v1, v1
	s_nop 0
	v_mul_f32_e32 v3, 0x3f317217, v1
	v_fma_f32 v3, v1, s77, -v3
	v_fmac_f32_e32 v3, 0x3377d1cf, v1
	v_fmac_f32_e32 v3, 0x3f317217, v1
	v_mov_b32_e32 v12, v3
	v_add_f32_e32 v1, 1.0, v198
	v_log_f32_e32 v1, v1
	s_nop 0
	v_mul_f32_e32 v3, 0x3f317217, v1
	v_fma_f32 v3, v1, s77, -v3
	v_fmac_f32_e32 v3, 0x3377d1cf, v1
	v_fmac_f32_e32 v3, 0x3f317217, v1
	v_mov_b32_e32 v14, v3
	v_add_f32_e32 v1, 1.0, v197
	v_log_f32_e32 v1, v1
	s_nop 0
	v_mul_f32_e32 v3, 0x3f317217, v1
	v_fma_f32 v3, v1, s77, -v3
	v_fmac_f32_e32 v3, 0x3377d1cf, v1
	v_fmac_f32_e32 v3, 0x3f317217, v1
	v_mov_b32_e32 v16, v3
	v_add_f32_e32 v1, 1.0, v196
	v_log_f32_e32 v1, v1
	s_nop 0
	v_mul_f32_e32 v3, 0x3f317217, v1
	v_fma_f32 v3, v1, s77, -v3
	v_fmac_f32_e32 v3, 0x3377d1cf, v1
	v_fmac_f32_e32 v3, 0x3f317217, v1
	v_mov_b32_e32 v18, v3
	v_add_f32_e32 v1, 1.0, v195
	v_log_f32_e32 v1, v1
	s_nop 0
	v_mul_f32_e32 v3, 0x3f317217, v1
	v_fma_f32 v3, v1, s77, -v3
	v_fmac_f32_e32 v3, 0x3377d1cf, v1
	v_fmac_f32_e32 v3, 0x3f317217, v1
	v_mov_b32_e32 v17, v3
	v_add_f32_e32 v1, 1.0, v194
	v_pk_add_f32 v[24:25], v[172:173], v[16:17]
	v_log_f32_e32 v1, v1
	s_nop 0
	v_mul_f32_e32 v3, 0x3f317217, v1
	v_fma_f32 v3, v1, s77, -v3
	v_fmac_f32_e32 v3, 0x3377d1cf, v1
	v_fmac_f32_e32 v3, 0x3f317217, v1
	v_mov_b32_e32 v19, v3
	v_add_f32_e32 v1, 1.0, v193
	v_pk_add_f32 v[26:27], v[170:171], v[18:19]
	v_log_f32_e32 v1, v1
	v_pk_add_f32 v[16:17], v[26:27], v[24:25] neg_lo:[1,1] neg_hi:[1,1]
	v_mul_f32_e32 v3, 0x3f317217, v1
	v_fma_f32 v3, v1, s77, -v3
	v_fmac_f32_e32 v3, 0x3377d1cf, v1
	v_fmac_f32_e32 v3, 0x3f317217, v1
	v_pk_add_f32 v[16:17], v[16:17], v[16:17] op_sel:[0,1] op_sel_hi:[1,0]
	ds_bpermute_b32 v18, v181, v16
	v_mov_b32_e32 v20, v3
	v_add_f32_e32 v1, 1.0, v192
	s_waitcnt lgkmcnt(0)
; DI int crow(int i, int h) { return (i & 3) + 8 * (i >> 2) + 4 * h; }
; DI float shx32(float v) { return __shfl_xor(v, 32); }
; template <bool MASKED>
; DI void sb_weights(f32x16 (&Sx)[2], float& carry, int kt, int t, int h) {
; #pragma unroll
;     ...
;         float L[16];
; #pragma unroll
;         for (int i = 0; i < 16; ++i) {
;           const float z = Sx[mt][i];
;           const bool ok = !MASKED || (kt * 64 + mt * 32 + crow(i, h) < t);
;           const float sp = fmaxf(z, 0.f) + __logf(1.f + __expf(-fabsf(z)));
;           L[i] = ok ? -sp : 0.f;
;           Sx[mt][i] = ok ? (z - sp) : NEG;
;         }
;         float G[4], Go[4];
; #pragma unroll
;         for (int gg = 0; gg < 4; ++gg) { G[gg] = (L[4 * gg] + L[4 * gg + 1]) + (L[4 * gg + 2] + L[4 * gg + 3]); Go[gg] = shx32(G[gg]); }
;         float T[4];
;         T[3] = 0.f; T[2] = G[3] + Go[3]; T[1] = T[2] + (G[2] + Go[2]); T[0] = T[1] + (G[1] + Go[1]);
;         const float tot = T[0] + (G[0] + Go[0]);
; #pragma unroll
;         for (int gg = 0; gg < 4; ++gg) {
;           const float s3 = carry + T[gg] + (h ? 0.f : Go[gg]);
;           const float s2 = s3 + L[4 * gg + 3], s1 = s2 + L[4 * gg + 2], s0 = s1 + L[4 * gg + 1];
;           Sx[mt][4 * gg + 3] = __expf(Sx[mt][4 * gg + 3] + s3);
;           Sx[mt][4 * gg + 2] = __expf(Sx[mt][4 * gg + 2] + s2);
;           Sx[mt][4 * gg + 1] = __expf(Sx[mt][4 * gg + 1] + s1);
;           Sx[mt][4 * gg + 0] = __expf(Sx[mt][4 * gg + 0] + s0);
;         }
;         carry += tot;
	v_cndmask_b32_e32 v9, 0, v18, vcc
	v_log_f32_e32 v1, v1
	s_nop 0
	v_mul_f32_e32 v3, 0x3f317217, v1
	v_fma_f32 v3, v1, s77, -v3
	v_fmac_f32_e32 v3, 0x3377d1cf, v1
	v_fmac_f32_e32 v3, 0x3f317217, v1
	v_mov_b32_e32 v22, v3
	v_add_f32_e32 v1, 1.0, v191
	v_log_f32_e32 v1, v1
	s_nop 0
	v_mul_f32_e32 v3, 0x3f317217, v1
	v_fma_f32 v3, v1, s77, -v3
	v_fmac_f32_e32 v3, 0x3377d1cf, v1
	v_fmac_f32_e32 v3, 0x3f317217, v1
	v_mov_b32_e32 v21, v3
	v_add_f32_e32 v1, 1.0, v190
	v_pk_add_f32 v[20:21], v[168:169], v[20:21]
	v_log_f32_e32 v1, v1
	s_nop 0
	v_mul_f32_e32 v3, 0x3f317217, v1
	v_fma_f32 v3, v1, s77, -v3
	v_fmac_f32_e32 v3, 0x3377d1cf, v1
	v_fmac_f32_e32 v3, 0x3f317217, v1
	v_mov_b32_e32 v23, v3
	v_pk_add_f32 v[22:23], v[166:167], v[22:23]
	v_sub_f32_e32 v1, v93, v27
	v_pk_add_f32 v[28:29], v[22:23], v[20:21] neg_lo:[1,1] neg_hi:[1,1]
	v_sub_f32_e32 v3, v97, v23
	v_add_f32_e32 v5, v28, v29
	ds_bpermute_b32 v7, v181, v5
	v_mov_b32_e32 v28, v25
	v_mov_b32_e32 v29, v27
	v_mov_b32_e32 v27, v25
	v_mov_b32_e32 v25, v26
	s_waitcnt lgkmcnt(0)
	v_add_f32_e32 v166, v5, v7
	v_add_f32_e32 v5, v144, v166
	v_add_f32_e32 v93, v9, v5
	v_pk_add_f32 v[28:29], v[92:93], v[28:29] neg_lo:[0,1] neg_hi:[0,1]
	v_add_f32_e32 v1, v1, v93
	v_mov_b32_e32 v31, v29
	v_mul_f32_e32 v1, 0x3fb8aa3b, v1
	v_pk_add_f32 v[30:31], v[30:31], v[26:27] neg_lo:[0,1] neg_hi:[0,1]
	v_exp_f32_e32 v27, v1
	v_add_f32_e32 v1, v28, v29
	v_mul_f32_e32 v1, 0x3fb8aa3b, v1
	v_mov_b32_e32 v91, v31
	v_exp_f32_e32 v26, v1
	v_add_f32_e32 v1, v30, v31
	v_pk_add_f32 v[90:91], v[90:91], v[24:25] neg_lo:[0,1] neg_hi:[0,1]
	v_mul_f32_e32 v1, 0x3fb8aa3b, v1
	v_exp_f32_e32 v25, v1
	v_add_f32_e32 v1, v90, v91
	v_mul_f32_e32 v1, 0x3fb8aa3b, v1
	v_exp_f32_e32 v24, v1
	v_cndmask_b32_e32 v1, 0, v7, vcc
	v_add_f32_e32 v97, v188, v1
	v_mov_b32_e32 v28, v21
	v_mov_b32_e32 v29, v23
	v_pk_add_f32 v[28:29], v[96:97], v[28:29] neg_lo:[0,1] neg_hi:[0,1]
	v_add_f32_e32 v1, v3, v97
	v_mov_b32_e32 v30, v95
	v_mov_b32_e32 v31, v29
	v_mov_b32_e32 v23, v21
	v_mul_f32_e32 v1, 0x3fb8aa3b, v1
	v_pk_add_f32 v[90:91], v[30:31], v[22:23] neg_lo:[0,1] neg_hi:[0,1]
	v_exp_f32_e32 v31, v1
	v_add_f32_e32 v1, v28, v29
	v_mul_f32_e32 v1, 0x3fb8aa3b, v1
	v_mov_b32_e32 v95, v91
	v_mov_b32_e32 v21, v22
	v_exp_f32_e32 v30, v1
	v_add_f32_e32 v1, v90, v91
	v_pk_add_f32 v[20:21], v[94:95], v[20:21] neg_lo:[0,1] neg_hi:[0,1]
	v_mul_f32_e32 v1, 0x3fb8aa3b, v1
	v_exp_f32_e32 v29, v1
	v_add_f32_e32 v1, v20, v21
	v_mul_f32_e32 v1, 0x3fb8aa3b, v1
	v_exp_f32_e32 v28, v1
	v_add_f32_e32 v1, 1.0, v189
	v_log_f32_e32 v1, v1
	s_nop 0
	v_mul_f32_e32 v3, 0x3f317217, v1
	v_fma_f32 v3, v1, s77, -v3
	v_fmac_f32_e32 v3, 0x3377d1cf, v1
	v_fmac_f32_e32 v3, 0x3f317217, v1
	v_mov_b32_e32 v20, v3
	v_add_f32_e32 v1, 1.0, v187
	v_log_f32_e32 v1, v1
	s_nop 0
	v_mul_f32_e32 v3, 0x3f317217, v1
	v_fma_f32 v3, v1, s77, -v3
	v_fmac_f32_e32 v3, 0x3377d1cf, v1
	v_fmac_f32_e32 v3, 0x3f317217, v1
	v_mov_b32_e32 v22, v3
	v_add_f32_e32 v1, 1.0, v186
	v_log_f32_e32 v1, v1
	s_nop 0
	v_mul_f32_e32 v3, 0x3f317217, v1
	v_fma_f32 v3, v1, s77, -v3
	v_fmac_f32_e32 v3, 0x3377d1cf, v1
	v_fmac_f32_e32 v3, 0x3f317217, v1
	v_mov_b32_e32 v21, v3
	v_exp_f32_e32 v1, v185
	v_pk_add_f32 v[96:97], v[162:163], v[20:21]
	v_add_f32_e32 v1, 1.0, v1
	v_log_f32_e32 v1, v1
	s_nop 0
	v_mul_f32_e32 v3, 0x3f317217, v1
	v_fma_f32 v3, v1, s77, -v3
	v_fmac_f32_e32 v3, 0x3377d1cf, v1
	v_fmac_f32_e32 v3, 0x3f317217, v1
	v_mov_b32_e32 v23, v3
	v_exp_f32_e32 v1, v184
	v_pk_add_f32 v[162:163], v[164:165], v[22:23]
	v_add_f32_e32 v1, 1.0, v1
	v_pk_add_f32 v[20:21], v[162:163], v[96:97] neg_lo:[1,1] neg_hi:[1,1]
	v_sub_f32_e32 v170, v69, v163
	v_log_f32_e32 v1, v1
	s_nop 0
	v_mul_f32_e32 v3, 0x3f317217, v1
	v_fma_f32 v3, v1, s77, -v3
	v_fmac_f32_e32 v3, 0x3377d1cf, v1
	v_fmac_f32_e32 v3, 0x3f317217, v1
	v_mov_b32_e32 v1, v3
	v_exp_f32_e32 v3, v183
	v_pk_add_f32 v[160:161], v[160:161], v[0:1]
	v_add_f32_e32 v3, 1.0, v3
	v_log_f32_e32 v3, v3
	s_nop 0
	v_mul_f32_e32 v5, 0x3f317217, v3
	v_fma_f32 v5, v3, s77, -v5
	v_fmac_f32_e32 v5, 0x3377d1cf, v3
	v_fmac_f32_e32 v5, 0x3f317217, v3
	v_mov_b32_e32 v3, v5
	v_exp_f32_e32 v5, v182
	v_pk_add_f32 v[158:159], v[158:159], v[2:3]
	v_add_f32_e32 v5, 1.0, v5
	v_pk_add_f32 v[0:1], v[158:159], v[160:161] neg_lo:[1,1] neg_hi:[1,1]
	v_log_f32_e32 v5, v5
	s_nop 0
	v_mul_f32_e32 v7, 0x3f317217, v5
	v_fma_f32 v7, v5, s77, -v7
	v_fmac_f32_e32 v7, 0x3377d1cf, v5
	v_fmac_f32_e32 v7, 0x3f317217, v5
	v_mov_b32_e32 v5, v7
	v_exp_f32_e32 v7, v153
	v_max_f32_e32 v153, 0, v151
	v_max_f32_e32 v151, 0, v147
	v_pk_add_f32 v[4:5], v[156:157], v[4:5]
	v_add_f32_e32 v7, 1.0, v7
	v_log_f32_e32 v7, v7
	s_nop 0
	v_mul_f32_e32 v9, 0x3f317217, v7
	v_fma_f32 v9, v7, s77, -v9
	v_fmac_f32_e32 v9, 0x3377d1cf, v7
	v_fmac_f32_e32 v9, 0x3f317217, v7
	v_mov_b32_e32 v7, v9
	v_exp_f32_e32 v9, v149
	v_pk_add_f32 v[6:7], v[154:155], v[6:7]
	v_add_f32_e32 v9, 1.0, v9
	v_pk_add_f32 v[2:3], v[6:7], v[4:5] neg_lo:[1,1] neg_hi:[1,1]
	v_sub_f32_e32 v171, v85, v6
	v_log_f32_e32 v9, v9
	v_pk_add_f32 v[0:1], v[0:1], v[2:3]
	ds_bpermute_b32 v2, v181, v0
	ds_bpermute_b32 v3, v181, v1
	v_mul_f32_e32 v11, 0x3f317217, v9
	v_fma_f32 v11, v9, s77, -v11
	v_fmac_f32_e32 v11, 0x3377d1cf, v9
	v_fmac_f32_e32 v11, 0x3f317217, v9
	s_waitcnt lgkmcnt(1)
	v_cndmask_b32_e32 v85, 0, v2, vcc
	s_waitcnt lgkmcnt(0)
; DI int crow(int i, int h) { return (i & 3) + 8 * (i >> 2) + 4 * h; }
; DI float shx32(float v) { return __shfl_xor(v, 32); }
; template <bool MASKED>
; DI void sb_weights(f32x16 (&Sx)[2], float& carry, int kt, int t, int h) {
; #pragma unroll
;     ...
;         float L[16];
; #pragma unroll
;         for (int i = 0; i < 16; ++i) {
;           const float z = Sx[mt][i];
;           const bool ok = !MASKED || (kt * 64 + mt * 32 + crow(i, h) < t);
;           const float sp = fmaxf(z, 0.f) + __logf(1.f + __expf(-fabsf(z)));
;           L[i] = ok ? -sp : 0.f;
;           Sx[mt][i] = ok ? (z - sp) : NEG;
;         }
;         float G[4], Go[4];
; #pragma unroll
;         for (int gg = 0; gg < 4; ++gg) { G[gg] = (L[4 * gg] + L[4 * gg + 1]) + (L[4 * gg + 2] + L[4 * gg + 3]); Go[gg] = shx32(G[gg]); }
;         float T[4];
;         T[3] = 0.f; T[2] = G[3] + Go[3]; T[1] = T[2] + (G[2] + Go[2]); T[0] = T[1] + (G[1] + Go[1]);
;         const float tot = T[0] + (G[0] + Go[0]);
; #pragma unroll
;         for (int gg = 0; gg < 4; ++gg) {
;           const float s3 = carry + T[gg] + (h ? 0.f : Go[gg]);
;           const float s2 = s3 + L[4 * gg + 3], s1 = s2 + L[4 * gg + 2], s0 = s1 + L[4 * gg + 1];
;           Sx[mt][4 * gg + 3] = __expf(Sx[mt][4 * gg + 3] + s3);
;           Sx[mt][4 * gg + 2] = __expf(Sx[mt][4 * gg + 2] + s2);
;           Sx[mt][4 * gg + 1] = __expf(Sx[mt][4 * gg + 1] + s1);
;           Sx[mt][4 * gg + 0] = __expf(Sx[mt][4 * gg + 0] + s0);
;         }
;         carry += tot;
	v_pk_add_f32 v[0:1], v[0:1], v[2:3]
	v_mov_b32_e32 v9, v11
	v_exp_f32_e32 v11, v145
	v_pk_add_f32 v[8:9], v[152:153], v[8:9]
	v_add_f32_e32 v11, 1.0, v11
	v_mov_b32_e32 v156, v8
	v_log_f32_e32 v11, v11
	s_nop 0
	v_mul_f32_e32 v13, 0x3f317217, v11
	v_fma_f32 v13, v11, s77, -v13
	v_fmac_f32_e32 v13, 0x3377d1cf, v11
	v_fmac_f32_e32 v13, 0x3f317217, v11
	v_mov_b32_e32 v11, v13
	v_max_f32_e32 v13, v76, v76
	v_max_f32_e32 v149, 0, v13
	v_mul_f32_e64 v13, |v76|, s76
	v_exp_f32_e32 v13, v13
	v_pk_add_f32 v[10:11], v[150:151], v[10:11]
	v_mov_b32_e32 v150, v160
	v_mov_b32_e32 v151, v158
	v_add_f32_e32 v13, 1.0, v13
	v_mov_b32_e32 v154, v10
	v_mov_b32_e32 v157, v10
	v_log_f32_e32 v13, v13
	s_nop 0
	v_mul_f32_e32 v15, 0x3f317217, v13
	v_fma_f32 v15, v13, s77, -v15
	v_fmac_f32_e32 v15, 0x3377d1cf, v13
	v_fmac_f32_e32 v15, 0x3f317217, v13
	v_mov_b32_e32 v13, v15
	v_max_f32_e32 v15, v77, v77
	v_max_f32_e32 v147, 0, v15
	v_mul_f32_e64 v15, |v77|, s76
	v_exp_f32_e32 v15, v15
	v_pk_add_f32 v[12:13], v[148:149], v[12:13]
	v_mov_b32_e32 v148, v158
	v_mov_b32_e32 v149, v4
	v_add_f32_e32 v15, 1.0, v15
	v_mov_b32_e32 v152, v12
	v_mov_b32_e32 v155, v12
	v_log_f32_e32 v15, v15
	v_mov_b32_e32 v158, v161
	v_mul_f32_e32 v17, 0x3f317217, v15
	v_fma_f32 v17, v15, s77, -v17
	v_fmac_f32_e32 v17, 0x3377d1cf, v15
	v_fmac_f32_e32 v17, 0x3f317217, v15
	v_mov_b32_e32 v15, v17
	v_max_f32_e32 v17, v78, v78
	v_max_f32_e32 v90, 0, v17
	v_mul_f32_e64 v17, |v78|, s76
	v_exp_f32_e32 v17, v17
	v_pk_add_f32 v[14:15], v[146:147], v[14:15]
	v_mov_b32_e32 v147, v6
	v_pk_add_f32 v[22:23], v[14:15], v[12:13] neg_lo:[1,1] neg_hi:[1,1]
	v_add_f32_e32 v17, 1.0, v17
	v_cndmask_b32_e32 v6, 0, v3, vcc
	v_mov_b32_e32 v146, v4
	v_log_f32_e32 v17, v17
	v_sub_f32_e32 v172, v89, v14
	v_mov_b32_e32 v153, v14
	v_sub_f32_e32 v160, v77, v15
	v_mul_f32_e32 v19, 0x3f317217, v17
	v_fma_f32 v19, v17, s77, -v19
	v_fmac_f32_e32 v19, 0x3377d1cf, v17
	v_fmac_f32_e32 v19, 0x3f317217, v17
	v_mov_b32_e32 v14, v13
	v_mov_b32_e32 v92, v19
	v_max_f32_e32 v17, v79, v79
	v_max_f32_e32 v91, 0, v17
	v_mul_f32_e64 v17, |v79|, s76
	v_exp_f32_e32 v17, v17
	s_nop 0
	v_add_f32_e32 v17, 1.0, v17
	v_log_f32_e32 v17, v17
	s_nop 0
	v_mul_f32_e32 v19, 0x3f317217, v17
	v_fma_f32 v19, v17, s77, -v19
	v_fmac_f32_e32 v19, 0x3377d1cf, v17
	v_fmac_f32_e32 v19, 0x3f317217, v17
	v_mov_b32_e32 v93, v19
	v_max_f32_e32 v17, v80, v80
	v_max_f32_e32 v94, 0, v17
	v_mul_f32_e64 v17, |v80|, s76
	v_exp_f32_e32 v17, v17
	v_pk_add_f32 v[90:91], v[90:91], v[92:93]
	v_add_f32_e32 v17, 1.0, v17
	v_log_f32_e32 v17, v17
	s_nop 0
	v_mul_f32_e32 v19, 0x3f317217, v17
	v_fma_f32 v19, v17, s77, -v19
	v_fmac_f32_e32 v19, 0x3377d1cf, v17
	v_fmac_f32_e32 v19, 0x3f317217, v17
	v_mov_b32_e32 v168, v19
	v_max_f32_e32 v17, v81, v81
	v_max_f32_e32 v95, 0, v17
	v_mul_f32_e64 v17, |v81|, s76
	v_exp_f32_e32 v17, v17
	s_nop 0
	v_add_f32_e32 v17, 1.0, v17
	v_log_f32_e32 v17, v17
	s_nop 0
	v_mul_f32_e32 v19, 0x3f317217, v17
	v_fma_f32 v19, v17, s77, -v19
	v_fmac_f32_e32 v19, 0x3377d1cf, v17
	v_fmac_f32_e32 v19, 0x3f317217, v17
	v_mov_b32_e32 v169, v19
	v_add_f32_e32 v17, v20, v21
	ds_bpermute_b32 v19, v181, v17
	v_pk_add_f32 v[94:95], v[94:95], v[168:169]
	v_pk_add_f32 v[20:21], v[10:11], v[8:9] neg_lo:[1,1] neg_hi:[1,1]
	v_sub_f32_e32 v8, v73, v7
	v_pk_add_f32 v[20:21], v[20:21], v[22:23]
	s_waitcnt lgkmcnt(0)
	v_add_f32_e32 v145, v17, v19
	v_cndmask_b32_e32 v69, 0, v19, vcc
	v_sub_f32_e64 v19, -v95, v94
	v_sub_f32_e64 v17, -v91, v90
	v_pk_add_f32 v[2:3], v[16:17], v[18:19]
	ds_bpermute_b32 v22, v181, v20
	ds_bpermute_b32 v23, v181, v21
	ds_bpermute_b32 v167, v181, v3
	v_mov_b32_e32 v16, v83
	v_sub_f32_e32 v168, v81, v95
	s_waitcnt lgkmcnt(2)
	v_cndmask_b32_e32 v4, 0, v22, vcc
	s_waitcnt lgkmcnt(1)
	v_pk_add_f32 v[20:21], v[20:21], v[22:23]
	s_waitcnt lgkmcnt(0)
; DI float shx32(float v) { return __shfl_xor(v, 32); }
; template <bool MASKED>
; DI void sb_weights(f32x16 (&Sx)[2], float& carry, int kt, int t, int h) {
;     ...
;         float G[4], Go[4];
; #pragma unroll
;         for (int gg = 0; gg < 4; ++gg) { G[gg] = (L[4 * gg] + L[4 * gg + 1]) + (L[4 * gg + 2] + L[4 * gg + 3]); Go[gg] = shx32(G[gg]); }
;         float T[4];
;         T[3] = 0.f; T[2] = G[3] + Go[3]; T[1] = T[2] + (G[2] + Go[2]); T[0] = T[1] + (G[1] + Go[1]);
;         const float tot = T[0] + (G[0] + Go[0]);
; #pragma unroll
;         for (int gg = 0; gg < 4; ++gg) {
;           const float s3 = carry + T[gg] + (h ? 0.f : Go[gg]);
;           const float s2 = s3 + L[4 * gg + 3], s1 = s2 + L[4 * gg + 2], s0 = s1 + L[4 * gg + 1];
;           Sx[mt][4 * gg + 3] = __expf(Sx[mt][4 * gg + 3] + s3);
;           Sx[mt][4 * gg + 2] = __expf(Sx[mt][4 * gg + 2] + s2);
;           Sx[mt][4 * gg + 1] = __expf(Sx[mt][4 * gg + 1] + s1);
;           Sx[mt][4 * gg + 0] = __expf(Sx[mt][4 * gg + 0] + s0);
;         }
;         carry += tot;
	v_pk_add_f32 v[92:93], v[2:3], v[166:167]
	v_cndmask_b32_e32 v10, 0, v23, vcc
	v_pk_add_f32 v[164:165], v[20:21], v[92:93]
	s_nop 0
	v_add_f32_e32 v2, v144, v164
	v_add_f32_e32 v85, v85, v2
	v_pk_add_f32 v[2:3], v[84:85], v[146:147] neg_lo:[0,1] neg_hi:[0,1]
	v_pk_add_f32 v[0:1], v[0:1], v[164:165]
	v_mov_b32_e32 v17, v3
	v_add_f32_e32 v2, v2, v3
	v_pk_add_f32 v[16:17], v[16:17], v[148:149] neg_lo:[0,1] neg_hi:[0,1]
	v_mul_f32_e32 v2, 0x3fb8aa3b, v2
	v_mov_b32_e32 v83, v17
	v_exp_f32_e32 v18, v2
	v_add_f32_e32 v2, v16, v17
	v_pk_add_f32 v[20:21], v[82:83], v[150:151] neg_lo:[0,1] neg_hi:[0,1]
	v_mul_f32_e32 v2, 0x3fb8aa3b, v2
	v_exp_f32_e32 v17, v2
	v_add_f32_e32 v2, v20, v21
	v_mul_f32_e32 v2, 0x3fb8aa3b, v2
	v_exp_f32_e32 v16, v2
	v_add_f32_e32 v2, v144, v92
	v_add_f32_e32 v89, v4, v2
	v_pk_add_f32 v[2:3], v[88:89], v[152:153] neg_lo:[0,1] neg_hi:[0,1]
	v_mov_b32_e32 v20, v87
	v_mov_b32_e32 v21, v3
	v_add_f32_e32 v2, v2, v3
	v_pk_add_f32 v[20:21], v[20:21], v[154:155] neg_lo:[0,1] neg_hi:[0,1]
	v_mul_f32_e32 v2, 0x3fb8aa3b, v2
	v_mov_b32_e32 v87, v21
	v_exp_f32_e32 v22, v2
	v_add_f32_e32 v2, v20, v21
	v_pk_add_f32 v[82:83], v[86:87], v[156:157] neg_lo:[0,1] neg_hi:[0,1]
	v_mul_f32_e32 v2, 0x3fb8aa3b, v2
	v_exp_f32_e32 v21, v2
	v_add_f32_e32 v2, v82, v83
	v_pk_add_f32 v[82:83], v[144:145], v[0:1]
	v_mul_f32_e32 v2, 0x3fb8aa3b, v2
	v_add_f32_e32 v0, v82, v1
	v_add_f32_e32 v69, v69, v0
	v_mov_b32_e32 v0, v97
	v_mov_b32_e32 v1, v163
	v_pk_add_f32 v[0:1], v[68:69], v[0:1] neg_lo:[0,1] neg_hi:[0,1]
	v_exp_f32_e32 v20, v2
	v_mov_b32_e32 v2, v67
	v_mov_b32_e32 v3, v1
	v_mov_b32_e32 v163, v97
	v_add_f32_e32 v12, v171, v85
	v_add_f32_e32 v4, v172, v89
	v_pk_add_f32 v[84:85], v[2:3], v[162:163] neg_lo:[0,1] neg_hi:[0,1]
	v_add_f32_e32 v2, v170, v69
	v_add_f32_e32 v0, v0, v1
	v_mul_f32_e32 v4, 0x3fb8aa3b, v4
	v_mul_f32_e32 v2, 0x3fb8aa3b, v2
	v_mul_f32_e32 v0, 0x3fb8aa3b, v0
	v_exp_f32_e32 v23, v4
	v_mov_b32_e32 v67, v85
	v_mov_b32_e32 v97, v162
	v_exp_f32_e32 v3, v2
	v_exp_f32_e32 v2, v0
	v_add_f32_e32 v0, v84, v85
	v_add_f32_e32 v4, v82, v165
	v_pk_add_f32 v[66:67], v[66:67], v[96:97] neg_lo:[0,1] neg_hi:[0,1]
	v_mul_f32_e32 v0, 0x3fb8aa3b, v0
	v_add_f32_e32 v73, v6, v4
	v_mov_b32_e32 v6, v5
	v_exp_f32_e32 v1, v0
	v_add_f32_e32 v0, v66, v67
	v_pk_add_f32 v[66:67], v[72:73], v[6:7] neg_lo:[0,1] neg_hi:[0,1]
	v_mov_b32_e32 v6, v71
	v_mov_b32_e32 v7, v67
	v_mov_b32_e32 v4, v159
	v_pk_add_f32 v[4:5], v[6:7], v[4:5] neg_lo:[0,1] neg_hi:[0,1]
	v_add_f32_e32 v6, v8, v73
	v_add_f32_e32 v8, v93, v82
	v_add_f32_e32 v77, v10, v8
	v_mul_f32_e32 v12, 0x3fb8aa3b, v12
	v_mul_f32_e32 v6, 0x3fb8aa3b, v6
	v_pk_add_f32 v[14:15], v[76:77], v[14:15] neg_lo:[0,1] neg_hi:[0,1]
	v_exp_f32_e32 v19, v12
	v_exp_f32_e32 v7, v6
	v_add_f32_e32 v6, v66, v67
	v_mov_b32_e32 v66, v75
	v_mov_b32_e32 v67, v15
	v_mov_b32_e32 v12, v11
	v_pk_add_f32 v[12:13], v[66:67], v[12:13] neg_lo:[0,1] neg_hi:[0,1]
	v_add_f32_e32 v8, v160, v77
	v_mov_b32_e32 v75, v13
	v_mov_b32_e32 v10, v9
	v_mul_f32_e32 v8, 0x3fb8aa3b, v8
	v_pk_add_f32 v[66:67], v[74:75], v[10:11] neg_lo:[0,1] neg_hi:[0,1]
	v_exp_f32_e32 v11, v8
	v_add_f32_e32 v8, v14, v15
	v_mul_f32_e32 v8, 0x3fb8aa3b, v8
	v_exp_f32_e32 v10, v8
	v_add_f32_e32 v8, v12, v13
	v_add_f32_e32 v12, 0, v82
	v_cndmask_b32_e32 v13, 0, v167, vcc
	v_add_f32_e32 v81, v13, v12
	v_mul_f32_e32 v8, 0x3fb8aa3b, v8
	v_pk_add_f32 v[12:13], v[80:81], v[94:95] neg_lo:[0,1] neg_hi:[0,1]
	v_exp_f32_e32 v9, v8
	v_add_f32_e32 v8, v66, v67
	v_mov_b32_e32 v14, v79
	v_mov_b32_e32 v15, v13
	v_pk_mov_b32 v[66:67], v[90:91], v[94:95] op_sel:[1,0]
	v_add_f32_e32 v12, v12, v13
	v_pk_add_f32 v[66:67], v[14:15], v[66:67] neg_lo:[0,1] neg_hi:[0,1]
	v_add_f32_e32 v14, v168, v81
	v_mov_b32_e32 v71, v5
	v_add_f32_e32 v4, v4, v5
	v_mul_f32_e32 v14, 0x3fb8aa3b, v14
	v_mul_f32_e32 v12, 0x3fb8aa3b, v12
	v_pk_add_f32 v[68:69], v[70:71], v[158:159] neg_lo:[0,1] neg_hi:[0,1]
	v_mul_f32_e32 v4, 0x3fb8aa3b, v4
	v_mov_b32_e32 v79, v67
	v_exp_f32_e32 v15, v14
	v_exp_f32_e32 v14, v12
	v_add_f32_e32 v12, v66, v67
	v_exp_f32_e32 v5, v4
	v_add_f32_e32 v4, v68, v69
	v_pk_add_f32 v[68:69], v[78:79], v[90:91] neg_lo:[0,1] neg_hi:[0,1]
	v_mul_f32_e32 v12, 0x3fb8aa3b, v12
	v_exp_f32_e32 v13, v12
	v_add_f32_e32 v12, v68, v69
	v_mul_f32_e32 v0, 0x3fb8aa3b, v0
	v_mul_f32_e32 v6, 0x3fb8aa3b, v6
	v_mul_f32_e32 v4, 0x3fb8aa3b, v4
	v_mul_f32_e32 v8, 0x3fb8aa3b, v8
	v_mul_f32_e32 v12, 0x3fb8aa3b, v12
	v_exp_f32_e32 v0, v0
	v_exp_f32_e32 v6, v6
	v_exp_f32_e32 v4, v4
	v_exp_f32_e32 v8, v8
	v_exp_f32_e32 v12, v12
	v_add_f32_e32 v144, v82, v83
